# M3 conv-weight LDS tile XOR swizzle (swap 16B halves for d0>=64) to remove 2-way bank conflict on ds_read_b128 conv weight reads
# speedup vs baseline: 1.0037x; 1.0037x over previous
.LBB0_685:
	s_or_b64 exec, exec, s[0:1]
	v_mov_b32_e32 v135, v214
	s_andn2_b64 vcc, exec, s[52:53]
	s_waitcnt lgkmcnt(0)
	s_barrier
	s_cbranch_vccnz .LBB0_743
	s_movk_i32 s0, 0x400
	v_cmp_gt_i32_e32 vcc, s0, v135
	s_and_saveexec_b64 s[0:1], vcc
	v_readlane_b32 s4, v246, 4
	v_readlane_b32 s10, v246, 10
	v_readlane_b32 s11, v246, 11
	v_readlane_b32 s5, v246, 5
	v_readlane_b32 s6, v246, 6
	v_readlane_b32 s7, v246, 7
	v_readlane_b32 s8, v246, 8
	v_readlane_b32 s9, v246, 9
	v_readlane_b32 s12, v246, 12
	v_readlane_b32 s13, v246, 13
	v_readlane_b32 s14, v246, 14
	v_readlane_b32 s15, v246, 15
	v_readlane_b32 s16, v246, 16
	v_readlane_b32 s17, v246, 17
	v_readlane_b32 s18, v246, 18
	v_readlane_b32 s19, v246, 19
	s_cbranch_execz .LBB0_689
	v_bfe_u32 v0, v135, 4, 1
	v_xor_b32_e32 v0, v0, v135
	v_lshlrev_b32_e32 v0, 4, v0
	v_add_u32_e32 v2, 0xfffffe00, v135
	v_add_u32_e32 v3, 0x19000, v0
	v_lshlrev_b32_e32 v0, 2, v135
	s_mov_b64 s[2:3], 0
	s_movk_i32 s4, 0x1ff

.LBB0_721:
	s_or_b64 exec, exec, s[0:1]
	v_lshlrev_b32_e32 v2, 3, v157
	s_lshl_b32 s4, s59, 2
	v_and_b32_e32 v156, 0x78, v2
	s_add_i32 s0, s4, 0
	v_lshl_add_u32 v198, v156, 2, s0
	v_ashrrev_i32_e32 v160, 3, v157
	v_and_b32_e32 v159, -2, v160
	v_lshlrev_b32_e32 v2, 1, v156
	v_mad_u32_u24 v124, v159, s48, v2
	v_add_u32_e32 v125, 0x110, v124
	s_mov_b32 s0, 0xbfb8aa3b
	s_mov_b32 vcc_lo, 0x3db504f3
	v_bfe_u32 v126, v156, 6, 1
	v_lshlrev_b32_e32 v126, 4, v126
	v_add_u32_e32 v3, 0x19000, v198
	v_add_u32_e32 v2, v3, v126
	v_sub_u32_e32 v3, v3, v126
	v_add_u32_e32 v3, 16, v3
	ds_read_b128 v[162:165], v2
	ds_read_b128 v[166:169], v2 offset:4096
	ds_read_b128 v[170:173], v2 offset:8192
	ds_read_b128 v[174:177], v2 offset:12288
	v_lshlrev_b32_e32 v178, 16, v92
	v_and_b32_e32 v179, 0xffff0000, v92
	v_lshlrev_b32_e32 v180, 16, v93
	v_and_b32_e32 v181, 0xffff0000, v93
	v_lshlrev_b32_e32 v182, 16, v88
	v_and_b32_e32 v183, 0xffff0000, v88
	v_lshlrev_b32_e32 v184, 16, v89
	v_and_b32_e32 v185, 0xffff0000, v89
	v_lshlrev_b32_e32 v186, 16, v96
	v_and_b32_e32 v187, 0xffff0000, v96
	v_lshlrev_b32_e32 v188, 16, v97
	v_and_b32_e32 v189, 0xffff0000, v97
	v_lshlrev_b32_e32 v190, 16, v100
	v_and_b32_e32 v191, 0xffff0000, v100
	v_lshlrev_b32_e32 v192, 16, v101
	v_and_b32_e32 v193, 0xffff0000, v101
	v_lshlrev_b32_e32 v194, 16, v104
	v_and_b32_e32 v195, 0xffff0000, v104
	v_lshlrev_b32_e32 v196, 16, v105
	v_and_b32_e32 v197, 0xffff0000, v105
	s_waitcnt lgkmcnt(0)
	v_pk_mul_f32 v[108:109], v[162:163], v[178:179]
	v_pk_mul_f32 v[110:111], v[164:165], v[180:181]
	v_pk_mul_f32 v[112:113], v[162:163], v[182:183]
	v_pk_mul_f32 v[114:115], v[164:165], v[184:185]
	v_pk_mul_f32 v[116:117], v[166:167], v[182:183]
	v_pk_mul_f32 v[118:119], v[168:169], v[184:185]
	v_pk_mul_f32 v[120:121], v[166:167], v[186:187]
	v_pk_mul_f32 v[122:123], v[168:169], v[188:189]
	v_pk_add_f32 v[108:109], v[116:117], v[108:109]
	v_pk_add_f32 v[110:111], v[118:119], v[110:111]
	v_pk_add_f32 v[112:113], v[120:121], v[112:113]
	v_pk_add_f32 v[114:115], v[122:123], v[114:115]
	v_pk_mul_f32 v[116:117], v[170:171], v[186:187]
	v_pk_mul_f32 v[118:119], v[172:173], v[188:189]
	v_pk_mul_f32 v[120:121], v[170:171], v[190:191]
	v_pk_mul_f32 v[122:123], v[172:173], v[192:193]
	v_pk_add_f32 v[108:109], v[116:117], v[108:109]
	v_pk_add_f32 v[110:111], v[118:119], v[110:111]
	v_pk_add_f32 v[112:113], v[120:121], v[112:113]
	v_pk_add_f32 v[114:115], v[122:123], v[114:115]
	v_pk_mul_f32 v[116:117], v[174:175], v[190:191]
	v_pk_mul_f32 v[118:119], v[176:177], v[192:193]
	v_pk_mul_f32 v[120:121], v[174:175], v[194:195]
	v_pk_mul_f32 v[122:123], v[176:177], v[196:197]
	v_pk_add_f32 v[108:109], v[116:117], v[108:109]
	v_pk_add_f32 v[110:111], v[118:119], v[110:111]
	v_pk_add_f32 v[112:113], v[120:121], v[112:113]
	v_pk_add_f32 v[114:115], v[122:123], v[114:115]
	v_pk_mul_f32 v[116:117], v[108:109], s[0:1] op_sel_hi:[1,0]
	v_pk_mul_f32 v[118:119], v[110:111], s[0:1] op_sel_hi:[1,0]
	v_pk_mul_f32 v[120:121], v[112:113], s[0:1] op_sel_hi:[1,0]
	v_pk_mul_f32 v[122:123], v[114:115], s[0:1] op_sel_hi:[1,0]
	v_exp_f32_e32 v116, v116
	v_exp_f32_e32 v117, v117
	v_exp_f32_e32 v118, v118
	v_exp_f32_e32 v119, v119
	v_exp_f32_e32 v120, v120
	v_exp_f32_e32 v121, v121
	v_exp_f32_e32 v122, v122
	v_exp_f32_e32 v123, v123
	v_pk_add_f32 v[116:117], v[116:117], 1.0 op_sel_hi:[1,0]
	v_pk_add_f32 v[118:119], v[118:119], 1.0 op_sel_hi:[1,0]
	v_pk_add_f32 v[120:121], v[120:121], 1.0 op_sel_hi:[1,0]
	v_pk_add_f32 v[122:123], v[122:123], 1.0 op_sel_hi:[1,0]
	v_rcp_f32_e32 v116, v116
	v_rcp_f32_e32 v117, v117
	v_rcp_f32_e32 v118, v118
	v_rcp_f32_e32 v119, v119
	v_rcp_f32_e32 v120, v120
	v_rcp_f32_e32 v121, v121
	v_rcp_f32_e32 v122, v122
	v_rcp_f32_e32 v123, v123
	v_pk_mul_f32 v[92:93], v[108:109], v[116:117]
	v_pk_mul_f32 v[88:89], v[110:111], v[118:119]
	v_pk_mul_f32 v[96:97], v[112:113], v[120:121]
	v_pk_mul_f32 v[100:101], v[114:115], v[122:123]
	ds_read_b128 v[162:165], v3
	ds_read_b128 v[166:169], v3 offset:4096
	ds_read_b128 v[170:173], v3 offset:8192
	ds_read_b128 v[174:177], v3 offset:12288
	v_lshlrev_b32_e32 v178, 16, v94
	v_and_b32_e32 v179, 0xffff0000, v94
	v_lshlrev_b32_e32 v180, 16, v95
	v_and_b32_e32 v181, 0xffff0000, v95
	v_lshlrev_b32_e32 v182, 16, v90
	v_and_b32_e32 v183, 0xffff0000, v90
	v_lshlrev_b32_e32 v184, 16, v91
	v_and_b32_e32 v185, 0xffff0000, v91
	v_lshlrev_b32_e32 v186, 16, v98
	v_and_b32_e32 v187, 0xffff0000, v98
	v_lshlrev_b32_e32 v188, 16, v99
	v_and_b32_e32 v189, 0xffff0000, v99
	v_lshlrev_b32_e32 v190, 16, v102
	v_and_b32_e32 v191, 0xffff0000, v102
	v_lshlrev_b32_e32 v192, 16, v103
	v_and_b32_e32 v193, 0xffff0000, v103
	v_lshlrev_b32_e32 v194, 16, v106
	v_and_b32_e32 v195, 0xffff0000, v106
	v_lshlrev_b32_e32 v196, 16, v107
	v_and_b32_e32 v197, 0xffff0000, v107
	s_waitcnt lgkmcnt(0)
	v_pk_mul_f32 v[108:109], v[162:163], v[178:179]
	v_pk_mul_f32 v[110:111], v[164:165], v[180:181]
	v_pk_mul_f32 v[112:113], v[162:163], v[182:183]
	v_pk_mul_f32 v[114:115], v[164:165], v[184:185]
	v_pk_mul_f32 v[116:117], v[166:167], v[182:183]
	v_pk_mul_f32 v[118:119], v[168:169], v[184:185]
	v_pk_mul_f32 v[120:121], v[166:167], v[186:187]
	v_pk_mul_f32 v[122:123], v[168:169], v[188:189]
	v_pk_add_f32 v[108:109], v[116:117], v[108:109]
	v_pk_add_f32 v[110:111], v[118:119], v[110:111]
	v_pk_add_f32 v[112:113], v[120:121], v[112:113]
	v_pk_add_f32 v[114:115], v[122:123], v[114:115]
	v_pk_mul_f32 v[116:117], v[170:171], v[186:187]
	v_pk_mul_f32 v[118:119], v[172:173], v[188:189]
	v_pk_mul_f32 v[120:121], v[170:171], v[190:191]
	v_pk_mul_f32 v[122:123], v[172:173], v[192:193]
	v_pk_add_f32 v[108:109], v[116:117], v[108:109]
	v_pk_add_f32 v[110:111], v[118:119], v[110:111]
	v_pk_add_f32 v[112:113], v[120:121], v[112:113]
	v_pk_add_f32 v[114:115], v[122:123], v[114:115]
	v_pk_mul_f32 v[116:117], v[174:175], v[190:191]
	v_pk_mul_f32 v[118:119], v[176:177], v[192:193]
	v_pk_mul_f32 v[120:121], v[174:175], v[194:195]
	v_pk_mul_f32 v[122:123], v[176:177], v[196:197]
	v_pk_add_f32 v[108:109], v[116:117], v[108:109]
	v_pk_add_f32 v[110:111], v[118:119], v[110:111]
	v_pk_add_f32 v[112:113], v[120:121], v[112:113]
	v_pk_add_f32 v[114:115], v[122:123], v[114:115]
	v_pk_mul_f32 v[116:117], v[108:109], s[0:1] op_sel_hi:[1,0]
	v_pk_mul_f32 v[118:119], v[110:111], s[0:1] op_sel_hi:[1,0]
	v_pk_mul_f32 v[120:121], v[112:113], s[0:1] op_sel_hi:[1,0]
	v_pk_mul_f32 v[122:123], v[114:115], s[0:1] op_sel_hi:[1,0]
	v_exp_f32_e32 v116, v116
	v_exp_f32_e32 v117, v117
	v_exp_f32_e32 v118, v118
	v_exp_f32_e32 v119, v119
	v_exp_f32_e32 v120, v120
	v_exp_f32_e32 v121, v121
	v_exp_f32_e32 v122, v122
	v_exp_f32_e32 v123, v123
	v_pk_add_f32 v[116:117], v[116:117], 1.0 op_sel_hi:[1,0]
	v_pk_add_f32 v[118:119], v[118:119], 1.0 op_sel_hi:[1,0]
	v_pk_add_f32 v[120:121], v[120:121], 1.0 op_sel_hi:[1,0]
	v_pk_add_f32 v[122:123], v[122:123], 1.0 op_sel_hi:[1,0]
	v_rcp_f32_e32 v116, v116
	v_rcp_f32_e32 v117, v117
	v_rcp_f32_e32 v118, v118
	v_rcp_f32_e32 v119, v119
	v_rcp_f32_e32 v120, v120
	v_rcp_f32_e32 v121, v121
	v_rcp_f32_e32 v122, v122
	v_rcp_f32_e32 v123, v123
	v_pk_mul_f32 v[108:109], v[108:109], v[116:117]
	v_pk_mul_f32 v[110:111], v[110:111], v[118:119]
	v_pk_mul_f32 v[112:113], v[112:113], v[120:121]
	v_pk_mul_f32 v[114:115], v[114:115], v[122:123]
	v_cvt_pk_bf16_f32 v116, v92, v93
	v_cvt_pk_bf16_f32 v117, v88, v89
	v_cvt_pk_bf16_f32 v118, v108, v109
	v_cvt_pk_bf16_f32 v119, v110, v111
	v_cvt_pk_bf16_f32 v120, v96, v97
	v_cvt_pk_bf16_f32 v121, v100, v101
	v_cvt_pk_bf16_f32 v122, v112, v113
	v_cvt_pk_bf16_f32 v123, v114, v115
	ds_write_b128 v124, v[116:119]
	ds_write_b128 v125, v[120:123]
	v_add_u32_e32 v3, 0x19800, v198
	v_add_u32_e32 v2, v3, v126
	v_sub_u32_e32 v3, v3, v126
	v_add_u32_e32 v3, 16, v3
	ds_read_b128 v[162:165], v2
	ds_read_b128 v[166:169], v2 offset:4096
	ds_read_b128 v[170:173], v2 offset:8192
	ds_read_b128 v[174:177], v2 offset:12288
	v_lshlrev_b32_e32 v178, 16, v68
	v_and_b32_e32 v179, 0xffff0000, v68
	v_lshlrev_b32_e32 v180, 16, v69
	v_and_b32_e32 v181, 0xffff0000, v69
	v_lshlrev_b32_e32 v182, 16, v76
	v_and_b32_e32 v183, 0xffff0000, v76
	v_lshlrev_b32_e32 v184, 16, v77
	v_and_b32_e32 v185, 0xffff0000, v77
	v_lshlrev_b32_e32 v186, 16, v72
	v_and_b32_e32 v187, 0xffff0000, v72
	v_lshlrev_b32_e32 v188, 16, v73
	v_and_b32_e32 v189, 0xffff0000, v73
	v_lshlrev_b32_e32 v190, 16, v80
	v_and_b32_e32 v191, 0xffff0000, v80
	v_lshlrev_b32_e32 v192, 16, v81
	v_and_b32_e32 v193, 0xffff0000, v81
	v_lshlrev_b32_e32 v194, 16, v84
	v_and_b32_e32 v195, 0xffff0000, v84
	v_lshlrev_b32_e32 v196, 16, v85
	v_and_b32_e32 v197, 0xffff0000, v85
	s_waitcnt lgkmcnt(0)
	v_pk_mul_f32 v[108:109], v[162:163], v[178:179]
	v_pk_mul_f32 v[110:111], v[164:165], v[180:181]
	v_pk_mul_f32 v[112:113], v[162:163], v[182:183]
	v_pk_mul_f32 v[114:115], v[164:165], v[184:185]
	v_pk_mul_f32 v[116:117], v[166:167], v[182:183]
	v_pk_mul_f32 v[118:119], v[168:169], v[184:185]
	v_pk_mul_f32 v[120:121], v[166:167], v[186:187]
	v_pk_mul_f32 v[122:123], v[168:169], v[188:189]
	v_pk_add_f32 v[108:109], v[116:117], v[108:109]
	v_pk_add_f32 v[110:111], v[118:119], v[110:111]
	v_pk_add_f32 v[112:113], v[120:121], v[112:113]
	v_pk_add_f32 v[114:115], v[122:123], v[114:115]
	v_pk_mul_f32 v[116:117], v[170:171], v[186:187]
	v_pk_mul_f32 v[118:119], v[172:173], v[188:189]
	v_pk_mul_f32 v[120:121], v[170:171], v[190:191]
	v_pk_mul_f32 v[122:123], v[172:173], v[192:193]
	v_pk_add_f32 v[108:109], v[116:117], v[108:109]
	v_pk_add_f32 v[110:111], v[118:119], v[110:111]
	v_pk_add_f32 v[112:113], v[120:121], v[112:113]
	v_pk_add_f32 v[114:115], v[122:123], v[114:115]
	v_pk_mul_f32 v[116:117], v[174:175], v[190:191]
	v_pk_mul_f32 v[118:119], v[176:177], v[192:193]
	v_pk_mul_f32 v[120:121], v[174:175], v[194:195]
	v_pk_mul_f32 v[122:123], v[176:177], v[196:197]
	v_pk_add_f32 v[108:109], v[116:117], v[108:109]
	v_pk_add_f32 v[110:111], v[118:119], v[110:111]
	v_pk_add_f32 v[112:113], v[120:121], v[112:113]
	v_pk_add_f32 v[114:115], v[122:123], v[114:115]
	v_pk_mul_f32 v[116:117], v[108:109], s[0:1] op_sel_hi:[1,0]
	v_pk_mul_f32 v[118:119], v[110:111], s[0:1] op_sel_hi:[1,0]
	v_pk_mul_f32 v[120:121], v[112:113], s[0:1] op_sel_hi:[1,0]
	v_pk_mul_f32 v[122:123], v[114:115], s[0:1] op_sel_hi:[1,0]
	v_exp_f32_e32 v116, v116
	v_exp_f32_e32 v117, v117
	v_exp_f32_e32 v118, v118
	v_exp_f32_e32 v119, v119
	v_exp_f32_e32 v120, v120
	v_exp_f32_e32 v121, v121
	v_exp_f32_e32 v122, v122
	v_exp_f32_e32 v123, v123
	v_pk_add_f32 v[116:117], v[116:117], 1.0 op_sel_hi:[1,0]
	v_pk_add_f32 v[118:119], v[118:119], 1.0 op_sel_hi:[1,0]
	v_pk_add_f32 v[120:121], v[120:121], 1.0 op_sel_hi:[1,0]
	v_pk_add_f32 v[122:123], v[122:123], 1.0 op_sel_hi:[1,0]
	v_rcp_f32_e32 v116, v116
	v_rcp_f32_e32 v117, v117
	v_rcp_f32_e32 v118, v118
	v_rcp_f32_e32 v119, v119
	v_rcp_f32_e32 v120, v120
	v_rcp_f32_e32 v121, v121
	v_rcp_f32_e32 v122, v122
	v_rcp_f32_e32 v123, v123
	v_pk_mul_f32 v[68:69], v[108:109], v[116:117]
	v_pk_mul_f32 v[76:77], v[110:111], v[118:119]
	v_pk_mul_f32 v[72:73], v[112:113], v[120:121]
	v_pk_mul_f32 v[80:81], v[114:115], v[122:123]
	ds_read_b128 v[162:165], v3
	ds_read_b128 v[166:169], v3 offset:4096
	ds_read_b128 v[170:173], v3 offset:8192
	ds_read_b128 v[174:177], v3 offset:12288
	v_lshlrev_b32_e32 v178, 16, v70
	v_and_b32_e32 v179, 0xffff0000, v70
	v_lshlrev_b32_e32 v180, 16, v71
	v_and_b32_e32 v181, 0xffff0000, v71
	v_lshlrev_b32_e32 v182, 16, v78
	v_and_b32_e32 v183, 0xffff0000, v78
	v_lshlrev_b32_e32 v184, 16, v79
	v_and_b32_e32 v185, 0xffff0000, v79
	v_lshlrev_b32_e32 v186, 16, v74
	v_and_b32_e32 v187, 0xffff0000, v74
	v_lshlrev_b32_e32 v188, 16, v75
	v_and_b32_e32 v189, 0xffff0000, v75
	v_lshlrev_b32_e32 v190, 16, v82
	v_and_b32_e32 v191, 0xffff0000, v82
	v_lshlrev_b32_e32 v192, 16, v83
	v_and_b32_e32 v193, 0xffff0000, v83
	v_lshlrev_b32_e32 v194, 16, v86
	v_and_b32_e32 v195, 0xffff0000, v86
	v_lshlrev_b32_e32 v196, 16, v87
	v_and_b32_e32 v197, 0xffff0000, v87
	s_waitcnt lgkmcnt(0)
	v_pk_mul_f32 v[108:109], v[162:163], v[178:179]
	v_pk_mul_f32 v[110:111], v[164:165], v[180:181]
	v_pk_mul_f32 v[112:113], v[162:163], v[182:183]
	v_pk_mul_f32 v[114:115], v[164:165], v[184:185]
	v_pk_mul_f32 v[116:117], v[166:167], v[182:183]
	v_pk_mul_f32 v[118:119], v[168:169], v[184:185]
	v_pk_mul_f32 v[120:121], v[166:167], v[186:187]
	v_pk_mul_f32 v[122:123], v[168:169], v[188:189]
	v_pk_add_f32 v[108:109], v[116:117], v[108:109]
	v_pk_add_f32 v[110:111], v[118:119], v[110:111]
	v_pk_add_f32 v[112:113], v[120:121], v[112:113]
	v_pk_add_f32 v[114:115], v[122:123], v[114:115]
	v_pk_mul_f32 v[116:117], v[170:171], v[186:187]
	v_pk_mul_f32 v[118:119], v[172:173], v[188:189]
	v_pk_mul_f32 v[120:121], v[170:171], v[190:191]
	v_pk_mul_f32 v[122:123], v[172:173], v[192:193]
	v_pk_add_f32 v[108:109], v[116:117], v[108:109]
	v_pk_add_f32 v[110:111], v[118:119], v[110:111]
	v_pk_add_f32 v[112:113], v[120:121], v[112:113]
	v_pk_add_f32 v[114:115], v[122:123], v[114:115]
	v_pk_mul_f32 v[116:117], v[174:175], v[190:191]
	v_pk_mul_f32 v[118:119], v[176:177], v[192:193]
	v_pk_mul_f32 v[120:121], v[174:175], v[194:195]
	v_pk_mul_f32 v[122:123], v[176:177], v[196:197]
	v_pk_add_f32 v[108:109], v[116:117], v[108:109]
	v_pk_add_f32 v[110:111], v[118:119], v[110:111]
	v_pk_add_f32 v[112:113], v[120:121], v[112:113]
	v_pk_add_f32 v[114:115], v[122:123], v[114:115]
	v_pk_mul_f32 v[116:117], v[108:109], s[0:1] op_sel_hi:[1,0]
	v_pk_mul_f32 v[118:119], v[110:111], s[0:1] op_sel_hi:[1,0]
	v_pk_mul_f32 v[120:121], v[112:113], s[0:1] op_sel_hi:[1,0]
	v_pk_mul_f32 v[122:123], v[114:115], s[0:1] op_sel_hi:[1,0]
	v_exp_f32_e32 v116, v116
	v_exp_f32_e32 v117, v117
	v_exp_f32_e32 v118, v118
	v_exp_f32_e32 v119, v119
	v_exp_f32_e32 v120, v120
	v_exp_f32_e32 v121, v121
	v_exp_f32_e32 v122, v122
	v_exp_f32_e32 v123, v123
	v_pk_add_f32 v[116:117], v[116:117], 1.0 op_sel_hi:[1,0]
	v_pk_add_f32 v[118:119], v[118:119], 1.0 op_sel_hi:[1,0]
	v_pk_add_f32 v[120:121], v[120:121], 1.0 op_sel_hi:[1,0]
	v_pk_add_f32 v[122:123], v[122:123], 1.0 op_sel_hi:[1,0]
	v_rcp_f32_e32 v116, v116
	v_rcp_f32_e32 v117, v117
	v_rcp_f32_e32 v118, v118
	v_rcp_f32_e32 v119, v119
	v_rcp_f32_e32 v120, v120
	v_rcp_f32_e32 v121, v121
	v_rcp_f32_e32 v122, v122
	v_rcp_f32_e32 v123, v123
	v_pk_mul_f32 v[108:109], v[108:109], v[116:117]
	v_pk_mul_f32 v[110:111], v[110:111], v[118:119]
	v_pk_mul_f32 v[112:113], v[112:113], v[120:121]
	v_pk_mul_f32 v[114:115], v[114:115], v[122:123]
	v_pk_mul_f32 v[68:69], v[68:69], vcc op_sel_hi:[1,0]
	v_pk_mul_f32 v[76:77], v[76:77], vcc op_sel_hi:[1,0]
	v_pk_mul_f32 v[72:73], v[72:73], vcc op_sel_hi:[1,0]
	v_pk_mul_f32 v[80:81], v[80:81], vcc op_sel_hi:[1,0]
	v_pk_mul_f32 v[108:109], v[108:109], vcc op_sel_hi:[1,0]
	v_pk_mul_f32 v[110:111], v[110:111], vcc op_sel_hi:[1,0]
	v_pk_mul_f32 v[112:113], v[112:113], vcc op_sel_hi:[1,0]
	v_pk_mul_f32 v[114:115], v[114:115], vcc op_sel_hi:[1,0]
	v_cvt_pk_bf16_f32 v116, v68, v69
	v_cvt_pk_bf16_f32 v117, v76, v77
	v_cvt_pk_bf16_f32 v118, v108, v109
	v_cvt_pk_bf16_f32 v119, v110, v111
	v_cvt_pk_bf16_f32 v120, v72, v73
	v_cvt_pk_bf16_f32 v121, v80, v81
	v_cvt_pk_bf16_f32 v122, v112, v113
	v_cvt_pk_bf16_f32 v123, v114, v115
	ds_write_b128 v124, v[116:119] offset:17408
	ds_write_b128 v125, v[120:123] offset:17408
	v_cmp_gt_i32_e32 vcc, s49, v157
	s_and_saveexec_b64 s[0:1], vcc
	v_lshl_add_u32 v2, v157, 2, 0
	v_add_u32_e32 v2, 0x18500, v2
	ds_write_b32 v2, v158
	s_or_b64 exec, exec, s[0:1]
	v_ashrrev_i32_e32 v91, 6, v157
	v_ashrrev_i32_e32 v76, 7, v157
	v_and_b32_e32 v88, 15, v157
	v_lshlrev_b32_e32 v2, 1, v91
	v_lshlrev_b32_e32 v73, 4, v76
	v_and_b32_e32 v3, 48, v161
	v_and_b32_e32 v77, 2, v2
	v_or_b32_e32 v2, v73, v88
	v_add_u32_e32 v72, 0, v3
	v_mad_u64_u32 v[2:3], s[0:1], v2, s48, v[72:73]
	v_cmp_gt_i32_e64 s[14:15], v77, v76
	v_cmp_le_i32_e32 vcc, v77, v76
	v_lshl_or_b32 v80, v77, 4, v88
	v_mov_b32_e32 v68, 0
	v_mov_b32_e32 v69, 0
	v_mov_b32_e32 v70, 0
	v_mov_b32_e32 v71, 0
	s_waitcnt lgkmcnt(0)
	s_barrier
	s_and_saveexec_b64 s[0:1], vcc
	s_cbranch_execz .LBB0_725
	ds_read_b128 v[68:71], v2
	v_mad_u32_u24 v3, v80, s48, v72
	ds_read_b128 v[82:85], v2 offset:64
	ds_read_b128 v[92:95], v3 offset:17408
	ds_read_b128 v[96:99], v3 offset:17472
	s_waitcnt lgkmcnt(1)
	v_mfma_f32_16x16x32_bf16 v[68:71], v[68:71], v[92:95], 0
	ds_read_b128 v[92:95], v2 offset:128
	ds_read_b128 v[100:103], v2 offset:192
	s_waitcnt lgkmcnt(2)
	v_mfma_f32_16x16x32_bf16 v[68:71], v[82:85], v[96:99], v[68:71]
	ds_read_b128 v[82:85], v3 offset:17536
	ds_read_b128 v[96:99], v3 offset:17600
	s_waitcnt lgkmcnt(1)
	v_mfma_f32_16x16x32_bf16 v[68:71], v[92:95], v[82:85], v[68:71]
	s_waitcnt lgkmcnt(0)
	v_mfma_f32_16x16x32_bf16 v[68:71], v[100:103], v[96:99], v[68:71]
